# merge epilogue: gate logits loaded in two batches of 32 in flight (was 32 serialized load pairs); same arithmetic
# speedup vs baseline: 1.0419x; 1.0419x over previous
; #define MFMA(a, b, c) __builtin_amdgcn_mfma_f32_32x32x16_bf16((a), (b), (c), 0, 0, 0)
; DI float bf2f(bfr v) { return __uint_as_float(((unsigned)v) << 16); }
; template <int NI>
; DI void gemm_main(const bfr* __restrict__ A, int lda, const bfr* __restrict__ Bt, int ldb, int K, f32x16 (&acc)[2][NI], bfr* sA_, bfr* sB_) {
;     ...
;   for (int kt = 0; kt < nk; ++kt) {
;     asm volatile("s_waitcnt vmcnt(0)" ::: "memory");
;     __builtin_amdgcn_s_barrier();
;     const unsigned char* cur = base + (kt & 1) * BUFSZ;
;     bf16x8 af[4][2], bq[4][NI];
; #pragma unroll
;     for (int ks = 0; ks < 4; ++ks) {
;       const int so = ((y ^ (2 * ks)) << 4) + lane_off;
; #pragma unroll
;       for (int i = 0; i < 2; ++i) af[ks][i] = *(const bf16x8*)(cur + (wm * 32 + i * 16) * 256 + so);
; #pragma unroll
;       for (int i = 0; i < NI; ++i) bq[ks][i] = *(const bf16x8*)(cur + 16384 + (wn * 16 * NI + i * 16) * 256 + so);
;     }
;     __builtin_amdgcn_sched_barrier(0);
;     if (kt + 1 < nk) {
;       unsigned char* nxt = base + ((kt + 1) & 1) * BUFSZ;
;       stage_tile<128>(A + (kt + 1) * 64, lda, nxt, tid);
;       stage_tile<64 * NI>(Bt + (kt + 1) * 64, ldb, nxt + 16384, tid);
;     }
;     __builtin_amdgcn_sched_barrier(0);
; #pragma unroll
;     for (int ks = 0; ks < 4; ++ks)
; #pragma unroll
;       for (int mi = 0; mi < 2; ++mi)
; #pragma unroll
;         for (int ni = 0; ni < NI; ++ni) acc[mi][ni] = MFMA(af[ks][mi], bq[ks][ni], acc[mi][ni]);
; DI void phase_merge(const Params& p, int l, unsigned char* smem) {
;     ...
; #pragma unroll
;       for (int mi = 0; mi < 2; ++mi)
; #pragma unroll
;         for (int ni = 0; ni < 2; ++ni) {
;           int rbo = m0 + wm * 64 + mi * 32 + 4 * h;
;           asm volatile("" : "+v"(rbo));
;           const bfr* gp = P + (size_t)rbo * PLD + C_GATE + nb * 2048 + n0 + wn * 64 + ni * 32 + l31;
; #pragma unroll
;           for (int r = 0; r < 16; ++r) {
;             const float g = bf2f(gp[(size_t)((r & 3) + 8 * (r >> 2)) * PLD]);
.LBB0_561:
	s_add_i32 s38, s9, 0xffff8000
	s_and_b32 s38, s38, 0x8000
	v_add_u32_e32 v161, s38, v159
	v_or_b32_e32 v206, s38, v160
	v_add_u32_e32 v166, v161, v158
	v_add_u32_e32 v174, v206, v158
	v_add_u32_e32 v182, v161, v157
	v_add_u32_e32 v190, v206, v157
	v_add_u32_e32 v198, v161, v156
	v_add_u32_e32 v207, v206, v156
	v_add_u32_e32 v161, v161, v155
	s_waitcnt vmcnt(0)
	s_barrier
	s_waitcnt vmcnt(0)
	ds_read_b128 v[162:165], v166
	ds_read_b128 v[166:169], v166 offset:4096
	ds_read_b128 v[170:173], v174 offset:16384
	ds_read_b128 v[174:177], v174 offset:20480
	ds_read_b128 v[178:181], v182
	ds_read_b128 v[182:185], v182 offset:4096
	ds_read_b128 v[186:189], v190 offset:16384
	ds_read_b128 v[190:193], v190 offset:20480
	ds_read_b128 v[194:197], v198
	ds_read_b128 v[198:201], v198 offset:4096
	ds_read_b128 v[202:205], v207 offset:16384
	ds_read_b128 v[212:215], v207 offset:20480
	ds_read_b128 v[224:227], v161
	ds_read_b128 v[236:239], v161 offset:4096
	v_add_u32_e32 v161, v206, v155
	ds_read_b128 v[244:247], v161 offset:16384
	ds_read_b128 v[248:251], v161 offset:20480
	s_and_b32 s38, s9, 0x8000
	v_add_u32_e32 v161, s38, v65
	v_add_u32_e32 v208, s38, v67
	v_readfirstlane_b32 s39, v161
	v_lshl_add_u64 v[206:207], v[150:151], 0, s[18:19]
	s_mov_b32 m0, s39
	v_readfirstlane_b32 s39, v208
	v_add_u32_e32 v211, s38, v97
	global_load_lds_dwordx4 v[206:207], off
	v_lshl_add_u64 v[206:207], v[148:149], 0, s[18:19]
	s_mov_b32 m0, s39
	v_readfirstlane_b32 s39, v211
	v_add_u32_e32 v219, s38, v154
	global_load_lds_dwordx4 v[206:207], off
	v_lshl_add_u64 v[206:207], v[146:147], 0, s[18:19]
	s_mov_b32 m0, s39
	v_readfirstlane_b32 s39, v219
	v_add_u32_e32 v161, 0x4000, v161
	global_load_lds_dwordx4 v[206:207], off
	v_lshl_add_u64 v[206:207], v[144:145], 0, s[18:19]
	s_mov_b32 m0, s39
	v_readfirstlane_b32 s39, v161
	v_add_u32_e32 v161, 0x4000, v208
	global_load_lds_dwordx4 v[206:207], off
	v_lshl_add_u64 v[206:207], v[142:143], 0, s[18:19]
	s_mov_b32 m0, s39
	v_readfirstlane_b32 s39, v161
	v_add_u32_e32 v161, 0x4000, v211
	global_load_lds_dwordx4 v[206:207], off
	v_lshl_add_u64 v[206:207], v[140:141], 0, s[18:19]
	s_mov_b32 m0, s39
	v_readfirstlane_b32 s39, v161
	v_add_u32_e32 v161, 0x4000, v219
	global_load_lds_dwordx4 v[206:207], off
	v_lshl_add_u64 v[206:207], v[138:139], 0, s[18:19]
	s_mov_b32 m0, s39
	v_readfirstlane_b32 s39, v161
	global_load_lds_dwordx4 v[206:207], off
	v_lshl_add_u64 v[206:207], v[136:137], 0, s[18:19]
	s_mov_b32 m0, s39
	s_nop 0
	global_load_lds_dwordx4 v[206:207], off
	s_waitcnt lgkmcnt(0)
	v_mfma_f32_32x32x16_bf16 v[48:63], v[162:165], v[170:173], v[48:63]
	s_add_u32 s18, s18, 0x80
	s_addc_u32 s19, s19, 0
	s_add_i32 s9, s9, 0x8000
	s_cmpk_eq_i32 s18, 0x380
	v_mfma_f32_32x32x16_bf16 v[32:47], v[162:165], v[174:177], v[32:47]
	v_mfma_f32_32x32x16_bf16 v[16:31], v[166:169], v[170:173], v[16:31]
	v_mfma_f32_32x32x16_bf16 v[0:15], v[166:169], v[174:177], v[0:15]
	v_mfma_f32_32x32x16_bf16 v[48:63], v[178:181], v[186:189], v[48:63]
	v_mfma_f32_32x32x16_bf16 v[32:47], v[178:181], v[190:193], v[32:47]
	v_mfma_f32_32x32x16_bf16 v[16:31], v[182:185], v[186:189], v[16:31]
	v_mfma_f32_32x32x16_bf16 v[0:15], v[182:185], v[190:193], v[0:15]
	v_mfma_f32_32x32x16_bf16 v[48:63], v[194:197], v[202:205], v[48:63]
	v_mfma_f32_32x32x16_bf16 v[32:47], v[194:197], v[212:215], v[32:47]
	v_mfma_f32_32x32x16_bf16 v[16:31], v[198:201], v[202:205], v[16:31]
	v_mfma_f32_32x32x16_bf16 v[0:15], v[198:201], v[212:215], v[0:15]
	v_mfma_f32_32x32x16_bf16 v[48:63], v[224:227], v[244:247], v[48:63]
	v_mfma_f32_32x32x16_bf16 v[32:47], v[224:227], v[248:251], v[32:47]
	v_mfma_f32_32x32x16_bf16 v[16:31], v[236:239], v[244:247], v[16:31]
	v_mfma_f32_32x32x16_bf16 v[0:15], v[236:239], v[248:251], v[0:15]
	s_cbranch_scc0 .LBB0_561
	v_add_u32_e32 v65, s38, v159
	v_add_u32_e32 v67, s38, v160
	v_add_u32_e32 v97, v65, v158
	s_waitcnt vmcnt(0)
	s_barrier
	s_waitcnt vmcnt(0)
	ds_read_b128 v[136:139], v97
	ds_read_b128 v[140:143], v97 offset:4096
	v_add_u32_e32 v97, v67, v158
	ds_read_b128 v[144:147], v97 offset:16384
	ds_read_b128 v[148:151], v97 offset:20480
	v_add_u32_e32 v97, v65, v157
	ds_read_b128 v[158:161], v97
	ds_read_b128 v[162:165], v97 offset:4096
	v_add_u32_e32 v97, v67, v157
	ds_read_b128 v[166:169], v97 offset:16384
	ds_read_b128 v[170:173], v97 offset:20480
	v_add_u32_e32 v97, v65, v156
	ds_read_b128 v[174:177], v97
	ds_read_b128 v[178:181], v97 offset:4096
	v_add_u32_e32 v97, v67, v156
	v_add_u32_e32 v65, v65, v155
	ds_read_b128 v[182:185], v97 offset:16384
	ds_read_b128 v[186:189], v97 offset:20480
	ds_read_b128 v[190:193], v65
	ds_read_b128 v[194:197], v65 offset:4096
	v_add_u32_e32 v65, v67, v155
	ds_read_b128 v[154:157], v65 offset:16384
	ds_read_b128 v[198:201], v65 offset:20480
	s_lshl_b32 s44, s37, 12
	s_add_u32 s18, s44, s16
	v_lshlrev_b32_e32 v245, 15, v72
	v_add3_u32 v245, v245, s18, v64
	v_add_u32_e32 v245, v245, v66
	v_add_u32_e32 v246, 0x100000, v245
	v_add_u32_e32 v227, 0xcc04000, v245
	global_load_ushort v202, v227, s[4:5]
	global_load_ushort v227, v227, s[4:5] offset:64
	v_add_u32_e32 v228, 0xcc0c000, v245
	global_load_ushort v203, v228, s[4:5]
	global_load_ushort v228, v228, s[4:5] offset:64
	v_add_u32_e32 v229, 0xcc14000, v245
	global_load_ushort v204, v229, s[4:5]
	global_load_ushort v229, v229, s[4:5] offset:64
	v_add_u32_e32 v230, 0xcc1c000, v245
	global_load_ushort v205, v230, s[4:5]
	global_load_ushort v230, v230, s[4:5] offset:64
	v_add_u32_e32 v231, 0xcc44000, v245
	global_load_ushort v206, v231, s[4:5]
	global_load_ushort v231, v231, s[4:5] offset:64
	v_add_u32_e32 v232, 0xcc4c000, v245
	global_load_ushort v207, v232, s[4:5]
	global_load_ushort v232, v232, s[4:5] offset:64
	v_add_u32_e32 v233, 0xcc54000, v245
	global_load_ushort v211, v233, s[4:5]
	global_load_ushort v233, v233, s[4:5] offset:64
	v_add_u32_e32 v235, 0xcc5c000, v245
	global_load_ushort v212, v235, s[4:5]
	global_load_ushort v235, v235, s[4:5] offset:64
	v_add_u32_e32 v236, 0xcc84000, v245
	global_load_ushort v213, v236, s[4:5]
	global_load_ushort v236, v236, s[4:5] offset:64
	v_add_u32_e32 v237, 0xcc8c000, v245
	global_load_ushort v214, v237, s[4:5]
	global_load_ushort v237, v237, s[4:5] offset:64
	v_add_u32_e32 v238, 0xcc94000, v245
	global_load_ushort v215, v238, s[4:5]
	global_load_ushort v238, v238, s[4:5] offset:64
	v_add_u32_e32 v239, 0xcc9c000, v245
	global_load_ushort v219, v239, s[4:5]
	global_load_ushort v239, v239, s[4:5] offset:64
	v_add_u32_e32 v240, 0xccc4000, v245
	global_load_ushort v223, v240, s[4:5]
	global_load_ushort v240, v240, s[4:5] offset:64
	v_add_u32_e32 v241, 0xcccc000, v245
	global_load_ushort v224, v241, s[4:5]
	global_load_ushort v241, v241, s[4:5] offset:64
	v_add_u32_e32 v242, 0xccd4000, v245
	global_load_ushort v225, v242, s[4:5]
	global_load_ushort v242, v242, s[4:5] offset:64
	v_add_u32_e32 v244, 0xccdc000, v245
	global_load_ushort v226, v244, s[4:5]
	global_load_ushort v244, v244, s[4:5] offset:64
	s_waitcnt lgkmcnt(0)
; #define MFMA(a, b, c) __builtin_amdgcn_mfma_f32_32x32x16_bf16((a), (b), (c), 0, 0, 0)
; DI float bf2f(bfr v) { return __uint_as_float(((unsigned)v) << 16); }
; DI float sigmoidf_(float x) { return 1.f / (1.f + __expf(-x)); }
; template <int NI>
; DI void gemm_main(const bfr* __restrict__ A, int lda, const bfr* __restrict__ Bt, int ldb, int K, f32x16 (&acc)[2][NI], bfr* sA_, bfr* sB_) {
;     ...
; #pragma unroll
;     for (int ks = 0; ks < 4; ++ks)
; #pragma unroll
;       for (int mi = 0; mi < 2; ++mi)
; #pragma unroll
;         for (int ni = 0; ni < NI; ++ni) acc[mi][ni] = MFMA(af[ks][mi], bq[ks][ni], acc[mi][ni]);
; DI void phase_merge(const Params& p, int l, unsigned char* smem) {
;     ...
; #pragma unroll
;       for (int mi = 0; mi < 2; ++mi)
; #pragma unroll
;         for (int ni = 0; ni < 2; ++ni) {
;           int rbo = m0 + wm * 64 + mi * 32 + 4 * h;
;           asm volatile("" : "+v"(rbo));
;           const bfr* gp = P + (size_t)rbo * PLD + C_GATE + nb * 2048 + n0 + wn * 64 + ni * 32 + l31;
; #pragma unroll
;           for (int r = 0; r < 16; ++r) {
;             const float g = bf2f(gp[(size_t)((r & 3) + 8 * (r >> 2)) * PLD]);
;             tot[mi][ni][r] += sigmoidf_(g) * acc[mi][ni][r];
	v_mfma_f32_32x32x16_bf16 v[48:63], v[136:139], v[144:147], v[48:63]
	v_mfma_f32_32x32x16_bf16 v[48:63], v[158:161], v[166:169], v[48:63]
	v_mfma_f32_32x32x16_bf16 v[48:63], v[174:177], v[182:185], v[48:63]
	v_mfma_f32_32x32x16_bf16 v[48:63], v[190:193], v[154:157], v[48:63]
	v_mfma_f32_32x32x16_bf16 v[32:47], v[136:139], v[148:151], v[32:47]
	v_mfma_f32_32x32x16_bf16 v[32:47], v[158:161], v[170:173], v[32:47]
	v_mfma_f32_32x32x16_bf16 v[32:47], v[174:177], v[186:189], v[32:47]
	v_mfma_f32_32x32x16_bf16 v[32:47], v[190:193], v[198:201], v[32:47]
	v_mfma_f32_32x32x16_bf16 v[16:31], v[140:143], v[144:147], v[16:31]
	v_mfma_f32_32x32x16_bf16 v[16:31], v[162:165], v[166:169], v[16:31]
	v_mfma_f32_32x32x16_bf16 v[16:31], v[178:181], v[182:185], v[16:31]
	v_mfma_f32_32x32x16_bf16 v[16:31], v[194:197], v[154:157], v[16:31]
	v_mfma_f32_32x32x16_bf16 v[0:15], v[140:143], v[148:151], v[0:15]
	v_mfma_f32_32x32x16_bf16 v[0:15], v[162:165], v[170:173], v[0:15]
	v_mfma_f32_32x32x16_bf16 v[0:15], v[178:181], v[186:189], v[0:15]
	v_mfma_f32_32x32x16_bf16 v[0:15], v[194:197], v[198:201], v[0:15]
	v_add_u32_e32 v158, 0xcc04000, v246
	global_load_ushort v136, v158, s[4:5]
	global_load_ushort v158, v158, s[4:5] offset:64
	v_add_u32_e32 v159, 0xcc0c000, v246
	global_load_ushort v137, v159, s[4:5]
	global_load_ushort v159, v159, s[4:5] offset:64
	v_add_u32_e32 v160, 0xcc14000, v246
	global_load_ushort v138, v160, s[4:5]
	global_load_ushort v160, v160, s[4:5] offset:64
	v_add_u32_e32 v161, 0xcc1c000, v246
	global_load_ushort v139, v161, s[4:5]
	global_load_ushort v161, v161, s[4:5] offset:64
	v_add_u32_e32 v162, 0xcc44000, v246
	global_load_ushort v140, v162, s[4:5]
	global_load_ushort v162, v162, s[4:5] offset:64
	v_add_u32_e32 v163, 0xcc4c000, v246
	global_load_ushort v141, v163, s[4:5]
	global_load_ushort v163, v163, s[4:5] offset:64
	v_add_u32_e32 v164, 0xcc54000, v246
	global_load_ushort v142, v164, s[4:5]
	global_load_ushort v164, v164, s[4:5] offset:64
	v_add_u32_e32 v165, 0xcc5c000, v246
	global_load_ushort v143, v165, s[4:5]
	global_load_ushort v165, v165, s[4:5] offset:64
	v_add_u32_e32 v166, 0xcc84000, v246
	global_load_ushort v144, v166, s[4:5]
	global_load_ushort v166, v166, s[4:5] offset:64
	v_add_u32_e32 v167, 0xcc8c000, v246
	global_load_ushort v145, v167, s[4:5]
	global_load_ushort v167, v167, s[4:5] offset:64
	v_add_u32_e32 v168, 0xcc94000, v246
	global_load_ushort v146, v168, s[4:5]
	global_load_ushort v168, v168, s[4:5] offset:64
	v_add_u32_e32 v169, 0xcc9c000, v246
	global_load_ushort v147, v169, s[4:5]
	global_load_ushort v169, v169, s[4:5] offset:64
	v_add_u32_e32 v170, 0xccc4000, v246
	global_load_ushort v148, v170, s[4:5]
	global_load_ushort v170, v170, s[4:5] offset:64
	v_add_u32_e32 v171, 0xcccc000, v246
	global_load_ushort v149, v171, s[4:5]
	global_load_ushort v171, v171, s[4:5] offset:64
	v_add_u32_e32 v172, 0xccd4000, v246
	global_load_ushort v150, v172, s[4:5]
	global_load_ushort v172, v172, s[4:5] offset:64
	v_add_u32_e32 v173, 0xccdc000, v246
	global_load_ushort v151, v173, s[4:5]
	global_load_ushort v173, v173, s[4:5] offset:64
	s_waitcnt vmcnt(32)
	v_lshlrev_b32_e32 v202, 16, v202
	v_lshlrev_b32_e32 v203, 16, v203
	v_mul_f32_e32 v202, 0xbfb8aa3b, v202
	v_mul_f32_e32 v203, 0xbfb8aa3b, v203
	v_exp_f32_e32 v202, v202
	v_exp_f32_e32 v203, v203
	v_add_f32_e64 v202, v202, 1.0
	v_add_f32_e64 v203, v203, 1.0
	v_div_scale_f32 v174, s[18:19], v203, v203, 1.0
	v_rcp_f32_e32 v175, v174
	v_div_scale_f32 v176, vcc, 1.0, v203, 1.0
	v_fma_f32 v179, -v174, v175, 1.0
	v_fmac_f32_e32 v175, v179, v175
	v_mul_f32_e32 v177, v176, v175
	v_fma_f32 v178, -v174, v177, v176
	v_fmac_f32_e32 v177, v178, v175
	v_fma_f32 v174, -v174, v177, v176
	v_div_fmas_f32 v174, v174, v175, v177
	v_div_fixup_f32 v181, v174, v203, 1.0
	v_div_scale_f32 v174, s[18:19], v202, v202, 1.0
	v_rcp_f32_e32 v175, v174
	v_div_scale_f32 v176, vcc, 1.0, v202, 1.0
	v_fma_f32 v179, -v174, v175, 1.0
	v_fmac_f32_e32 v175, v179, v175
	v_mul_f32_e32 v177, v176, v175
	v_fma_f32 v178, -v174, v177, v176
	v_fmac_f32_e32 v177, v178, v175
	v_fma_f32 v174, -v174, v177, v176
	v_div_fmas_f32 v174, v174, v175, v177
	v_div_fixup_f32 v180, v174, v202, 1.0
	v_pk_fma_f32 v[134:135], v[48:49], v[180:181], v[134:135]
	v_lshlrev_b32_e32 v204, 16, v204
	v_lshlrev_b32_e32 v205, 16, v205
	v_mul_f32_e32 v204, 0xbfb8aa3b, v204
	v_mul_f32_e32 v205, 0xbfb8aa3b, v205
	v_exp_f32_e32 v204, v204
	v_exp_f32_e32 v205, v205
	v_add_f32_e64 v204, v204, 1.0
	v_add_f32_e64 v205, v205, 1.0
	v_div_scale_f32 v174, s[18:19], v205, v205, 1.0
	v_rcp_f32_e32 v175, v174
	v_div_scale_f32 v176, vcc, 1.0, v205, 1.0
	v_fma_f32 v179, -v174, v175, 1.0
	v_fmac_f32_e32 v175, v179, v175
	v_mul_f32_e32 v177, v176, v175
	v_fma_f32 v178, -v174, v177, v176
	v_fmac_f32_e32 v177, v178, v175
	v_fma_f32 v174, -v174, v177, v176
	v_div_fmas_f32 v174, v174, v175, v177
	v_div_fixup_f32 v181, v174, v205, 1.0
	v_div_scale_f32 v174, s[18:19], v204, v204, 1.0
	v_rcp_f32_e32 v175, v174
	v_div_scale_f32 v176, vcc, 1.0, v204, 1.0
	v_fma_f32 v179, -v174, v175, 1.0
	v_fmac_f32_e32 v175, v179, v175
	v_mul_f32_e32 v177, v176, v175
	v_fma_f32 v178, -v174, v177, v176
	v_fmac_f32_e32 v177, v178, v175
	v_fma_f32 v174, -v174, v177, v176
	v_div_fmas_f32 v174, v174, v175, v177
	v_div_fixup_f32 v180, v174, v204, 1.0
	v_pk_fma_f32 v[132:133], v[50:51], v[180:181], v[132:133]
	v_lshlrev_b32_e32 v206, 16, v206
	v_lshlrev_b32_e32 v207, 16, v207
	v_mul_f32_e32 v206, 0xbfb8aa3b, v206
	v_mul_f32_e32 v207, 0xbfb8aa3b, v207
	v_exp_f32_e32 v206, v206
	v_exp_f32_e32 v207, v207
	v_add_f32_e64 v206, v206, 1.0
	v_add_f32_e64 v207, v207, 1.0
	v_div_scale_f32 v174, s[18:19], v207, v207, 1.0
; DI float bf2f(bfr v) { return __uint_as_float(((unsigned)v) << 16); }
; DI float sigmoidf_(float x) { return 1.f / (1.f + __expf(-x)); }
; DI void phase_merge(const Params& p, int l, unsigned char* smem) {
;     ...
; #pragma unroll
;           for (int r = 0; r < 16; ++r) {
;             const float g = bf2f(gp[(size_t)((r & 3) + 8 * (r >> 2)) * PLD]);
;             tot[mi][ni][r] += sigmoidf_(g) * acc[mi][ni][r];
	v_rcp_f32_e32 v175, v174
	v_div_scale_f32 v176, vcc, 1.0, v207, 1.0
	v_fma_f32 v179, -v174, v175, 1.0
	v_fmac_f32_e32 v175, v179, v175
	v_mul_f32_e32 v177, v176, v175
	v_fma_f32 v178, -v174, v177, v176
	v_fmac_f32_e32 v177, v178, v175
	v_fma_f32 v174, -v174, v177, v176
	v_div_fmas_f32 v174, v174, v175, v177
	v_div_fixup_f32 v181, v174, v207, 1.0
	v_div_scale_f32 v174, s[18:19], v206, v206, 1.0
	v_rcp_f32_e32 v175, v174
	v_div_scale_f32 v176, vcc, 1.0, v206, 1.0
	v_fma_f32 v179, -v174, v175, 1.0
	v_fmac_f32_e32 v175, v179, v175
	v_mul_f32_e32 v177, v176, v175
	v_fma_f32 v178, -v174, v177, v176
	v_fmac_f32_e32 v177, v178, v175
	v_fma_f32 v174, -v174, v177, v176
	v_div_fmas_f32 v174, v174, v175, v177
	v_div_fixup_f32 v180, v174, v206, 1.0
	v_pk_fma_f32 v[130:131], v[52:53], v[180:181], v[130:131]
	v_lshlrev_b32_e32 v211, 16, v211
	v_lshlrev_b32_e32 v212, 16, v212
	v_mul_f32_e32 v211, 0xbfb8aa3b, v211
	v_mul_f32_e32 v212, 0xbfb8aa3b, v212
	v_exp_f32_e32 v211, v211
	v_exp_f32_e32 v212, v212
	v_add_f32_e64 v211, v211, 1.0
	v_add_f32_e64 v212, v212, 1.0
	v_div_scale_f32 v174, s[18:19], v212, v212, 1.0
	v_rcp_f32_e32 v175, v174
	v_div_scale_f32 v176, vcc, 1.0, v212, 1.0
	v_fma_f32 v179, -v174, v175, 1.0
	v_fmac_f32_e32 v175, v179, v175
	v_mul_f32_e32 v177, v176, v175
	v_fma_f32 v178, -v174, v177, v176
	v_fmac_f32_e32 v177, v178, v175
	v_fma_f32 v174, -v174, v177, v176
	v_div_fmas_f32 v174, v174, v175, v177
	v_div_fixup_f32 v181, v174, v212, 1.0
	v_div_scale_f32 v174, s[18:19], v211, v211, 1.0
	v_rcp_f32_e32 v175, v174
	v_div_scale_f32 v176, vcc, 1.0, v211, 1.0
	v_fma_f32 v179, -v174, v175, 1.0
	v_fmac_f32_e32 v175, v179, v175
	v_mul_f32_e32 v177, v176, v175
	v_fma_f32 v178, -v174, v177, v176
	v_fmac_f32_e32 v177, v178, v175
	v_fma_f32 v174, -v174, v177, v176
	v_div_fmas_f32 v174, v174, v175, v177
	v_div_fixup_f32 v180, v174, v211, 1.0
	v_pk_fma_f32 v[128:129], v[54:55], v[180:181], v[128:129]
	v_lshlrev_b32_e32 v213, 16, v213
	v_lshlrev_b32_e32 v214, 16, v214
	v_mul_f32_e32 v213, 0xbfb8aa3b, v213
	v_mul_f32_e32 v214, 0xbfb8aa3b, v214
	v_exp_f32_e32 v213, v213
	v_exp_f32_e32 v214, v214
	v_add_f32_e64 v213, v213, 1.0
	v_add_f32_e64 v214, v214, 1.0
	v_div_scale_f32 v174, s[18:19], v214, v214, 1.0
	v_rcp_f32_e32 v175, v174
	v_div_scale_f32 v176, vcc, 1.0, v214, 1.0
	v_fma_f32 v179, -v174, v175, 1.0
	v_fmac_f32_e32 v175, v179, v175
	v_mul_f32_e32 v177, v176, v175
	v_fma_f32 v178, -v174, v177, v176
	v_fmac_f32_e32 v177, v178, v175
	v_fma_f32 v174, -v174, v177, v176
	v_div_fmas_f32 v174, v174, v175, v177
	v_div_fixup_f32 v181, v174, v214, 1.0
	v_div_scale_f32 v174, s[18:19], v213, v213, 1.0
	v_rcp_f32_e32 v175, v174
	v_div_scale_f32 v176, vcc, 1.0, v213, 1.0
	v_fma_f32 v179, -v174, v175, 1.0
	v_fmac_f32_e32 v175, v179, v175
	v_mul_f32_e32 v177, v176, v175
	v_fma_f32 v178, -v174, v177, v176
	v_fmac_f32_e32 v177, v178, v175
	v_fma_f32 v174, -v174, v177, v176
	v_div_fmas_f32 v174, v174, v175, v177
	v_div_fixup_f32 v180, v174, v213, 1.0
	v_pk_fma_f32 v[126:127], v[56:57], v[180:181], v[126:127]
	v_lshlrev_b32_e32 v215, 16, v215
	v_lshlrev_b32_e32 v219, 16, v219
	v_mul_f32_e32 v215, 0xbfb8aa3b, v215
	v_mul_f32_e32 v219, 0xbfb8aa3b, v219
	v_exp_f32_e32 v215, v215
	v_exp_f32_e32 v219, v219
	v_add_f32_e64 v215, v215, 1.0
	v_add_f32_e64 v219, v219, 1.0
	v_div_scale_f32 v174, s[18:19], v219, v219, 1.0
	v_rcp_f32_e32 v175, v174
	v_div_scale_f32 v176, vcc, 1.0, v219, 1.0
	v_fma_f32 v179, -v174, v175, 1.0
	v_fmac_f32_e32 v175, v179, v175
	v_mul_f32_e32 v177, v176, v175
	v_fma_f32 v178, -v174, v177, v176
	v_fmac_f32_e32 v177, v178, v175
	v_fma_f32 v174, -v174, v177, v176
	v_div_fmas_f32 v174, v174, v175, v177
	v_div_fixup_f32 v181, v174, v219, 1.0
	v_div_scale_f32 v174, s[18:19], v215, v215, 1.0
	v_rcp_f32_e32 v175, v174
	v_div_scale_f32 v176, vcc, 1.0, v215, 1.0
	v_fma_f32 v179, -v174, v175, 1.0
	v_fmac_f32_e32 v175, v179, v175
	v_mul_f32_e32 v177, v176, v175
	v_fma_f32 v178, -v174, v177, v176
	v_fmac_f32_e32 v177, v178, v175
	v_fma_f32 v174, -v174, v177, v176
	v_div_fmas_f32 v174, v174, v175, v177
	v_div_fixup_f32 v180, v174, v215, 1.0
	v_pk_fma_f32 v[124:125], v[58:59], v[180:181], v[124:125]
	v_lshlrev_b32_e32 v223, 16, v223
	v_lshlrev_b32_e32 v224, 16, v224
	v_mul_f32_e32 v223, 0xbfb8aa3b, v223
	v_mul_f32_e32 v224, 0xbfb8aa3b, v224
	v_exp_f32_e32 v223, v223
	v_exp_f32_e32 v224, v224
	v_add_f32_e64 v223, v223, 1.0
	v_add_f32_e64 v224, v224, 1.0
	v_div_scale_f32 v174, s[18:19], v224, v224, 1.0
	v_rcp_f32_e32 v175, v174
	v_div_scale_f32 v176, vcc, 1.0, v224, 1.0
	v_fma_f32 v179, -v174, v175, 1.0
	v_fmac_f32_e32 v175, v179, v175
	v_mul_f32_e32 v177, v176, v175
	v_fma_f32 v178, -v174, v177, v176
	v_fmac_f32_e32 v177, v178, v175
	v_fma_f32 v174, -v174, v177, v176
	v_div_fmas_f32 v174, v174, v175, v177
	v_div_fixup_f32 v181, v174, v224, 1.0
	v_div_scale_f32 v174, s[18:19], v223, v223, 1.0
	v_rcp_f32_e32 v175, v174
	v_div_scale_f32 v176, vcc, 1.0, v223, 1.0
	v_fma_f32 v179, -v174, v175, 1.0
	v_fmac_f32_e32 v175, v179, v175
	v_mul_f32_e32 v177, v176, v175
	v_fma_f32 v178, -v174, v177, v176
	v_fmac_f32_e32 v177, v178, v175
	v_fma_f32 v174, -v174, v177, v176
	v_div_fmas_f32 v174, v174, v175, v177
	v_div_fixup_f32 v180, v174, v223, 1.0
	v_pk_fma_f32 v[122:123], v[60:61], v[180:181], v[122:123]
	v_lshlrev_b32_e32 v225, 16, v225
	v_lshlrev_b32_e32 v226, 16, v226
	v_mul_f32_e32 v225, 0xbfb8aa3b, v225
	v_mul_f32_e32 v226, 0xbfb8aa3b, v226
	v_exp_f32_e32 v225, v225
	v_exp_f32_e32 v226, v226
	v_add_f32_e64 v225, v225, 1.0
	v_add_f32_e64 v226, v226, 1.0
	v_div_scale_f32 v174, s[18:19], v226, v226, 1.0
	v_rcp_f32_e32 v175, v174
	v_div_scale_f32 v176, vcc, 1.0, v226, 1.0
; DI float bf2f(bfr v) { return __uint_as_float(((unsigned)v) << 16); }
; DI float sigmoidf_(float x) { return 1.f / (1.f + __expf(-x)); }
; DI void phase_merge(const Params& p, int l, unsigned char* smem) {
;     ...
; #pragma unroll
;           for (int r = 0; r < 16; ++r) {
;             const float g = bf2f(gp[(size_t)((r & 3) + 8 * (r >> 2)) * PLD]);
;             tot[mi][ni][r] += sigmoidf_(g) * acc[mi][ni][r];
	v_fma_f32 v179, -v174, v175, 1.0
	v_fmac_f32_e32 v175, v179, v175
	v_mul_f32_e32 v177, v176, v175
	v_fma_f32 v178, -v174, v177, v176
	v_fmac_f32_e32 v177, v178, v175
	v_fma_f32 v174, -v174, v177, v176
	v_div_fmas_f32 v174, v174, v175, v177
	v_div_fixup_f32 v181, v174, v226, 1.0
	v_div_scale_f32 v174, s[18:19], v225, v225, 1.0
	v_rcp_f32_e32 v175, v174
	v_div_scale_f32 v176, vcc, 1.0, v225, 1.0
	v_fma_f32 v179, -v174, v175, 1.0
	v_fmac_f32_e32 v175, v179, v175
	v_mul_f32_e32 v177, v176, v175
	v_fma_f32 v178, -v174, v177, v176
	v_fmac_f32_e32 v177, v178, v175
	v_fma_f32 v174, -v174, v177, v176
	v_div_fmas_f32 v174, v174, v175, v177
	v_div_fixup_f32 v180, v174, v225, 1.0
	v_pk_fma_f32 v[120:121], v[62:63], v[180:181], v[120:121]
	v_lshlrev_b32_e32 v227, 16, v227
	v_lshlrev_b32_e32 v228, 16, v228
	v_mul_f32_e32 v227, 0xbfb8aa3b, v227
	v_mul_f32_e32 v228, 0xbfb8aa3b, v228
	v_exp_f32_e32 v227, v227
	v_exp_f32_e32 v228, v228
	v_add_f32_e64 v227, v227, 1.0
	v_add_f32_e64 v228, v228, 1.0
	v_div_scale_f32 v174, s[18:19], v228, v228, 1.0
	v_rcp_f32_e32 v175, v174
	v_div_scale_f32 v176, vcc, 1.0, v228, 1.0
	v_fma_f32 v179, -v174, v175, 1.0
	v_fmac_f32_e32 v175, v179, v175
	v_mul_f32_e32 v177, v176, v175
	v_fma_f32 v178, -v174, v177, v176
	v_fmac_f32_e32 v177, v178, v175
	v_fma_f32 v174, -v174, v177, v176
	v_div_fmas_f32 v174, v174, v175, v177
	v_div_fixup_f32 v181, v174, v228, 1.0
	v_div_scale_f32 v174, s[18:19], v227, v227, 1.0
	v_rcp_f32_e32 v175, v174
	v_div_scale_f32 v176, vcc, 1.0, v227, 1.0
	v_fma_f32 v179, -v174, v175, 1.0
	v_fmac_f32_e32 v175, v179, v175
	v_mul_f32_e32 v177, v176, v175
	v_fma_f32 v178, -v174, v177, v176
	v_fmac_f32_e32 v177, v178, v175
	v_fma_f32 v174, -v174, v177, v176
	v_div_fmas_f32 v174, v174, v175, v177
	v_div_fixup_f32 v180, v174, v227, 1.0
	v_pk_fma_f32 v[118:119], v[32:33], v[180:181], v[118:119]
	v_lshlrev_b32_e32 v229, 16, v229
	v_lshlrev_b32_e32 v230, 16, v230
	v_mul_f32_e32 v229, 0xbfb8aa3b, v229
	v_mul_f32_e32 v230, 0xbfb8aa3b, v230
	v_exp_f32_e32 v229, v229
	v_exp_f32_e32 v230, v230
	v_add_f32_e64 v229, v229, 1.0
	v_add_f32_e64 v230, v230, 1.0
	v_div_scale_f32 v174, s[18:19], v230, v230, 1.0
	v_rcp_f32_e32 v175, v174
	v_div_scale_f32 v176, vcc, 1.0, v230, 1.0
	v_fma_f32 v179, -v174, v175, 1.0
	v_fmac_f32_e32 v175, v179, v175
	v_mul_f32_e32 v177, v176, v175
	v_fma_f32 v178, -v174, v177, v176
	v_fmac_f32_e32 v177, v178, v175
	v_fma_f32 v174, -v174, v177, v176
	v_div_fmas_f32 v174, v174, v175, v177
	v_div_fixup_f32 v181, v174, v230, 1.0
	v_div_scale_f32 v174, s[18:19], v229, v229, 1.0
	v_rcp_f32_e32 v175, v174
	v_div_scale_f32 v176, vcc, 1.0, v229, 1.0
	v_fma_f32 v179, -v174, v175, 1.0
	v_fmac_f32_e32 v175, v179, v175
	v_mul_f32_e32 v177, v176, v175
	v_fma_f32 v178, -v174, v177, v176
	v_fmac_f32_e32 v177, v178, v175
	v_fma_f32 v174, -v174, v177, v176
	v_div_fmas_f32 v174, v174, v175, v177
	v_div_fixup_f32 v180, v174, v229, 1.0
	v_pk_fma_f32 v[116:117], v[34:35], v[180:181], v[116:117]
	v_lshlrev_b32_e32 v231, 16, v231
	v_lshlrev_b32_e32 v232, 16, v232
	v_mul_f32_e32 v231, 0xbfb8aa3b, v231
	v_mul_f32_e32 v232, 0xbfb8aa3b, v232
	v_exp_f32_e32 v231, v231
	v_exp_f32_e32 v232, v232
	v_add_f32_e64 v231, v231, 1.0
	v_add_f32_e64 v232, v232, 1.0
	v_div_scale_f32 v174, s[18:19], v232, v232, 1.0
	v_rcp_f32_e32 v175, v174
	v_div_scale_f32 v176, vcc, 1.0, v232, 1.0
	v_fma_f32 v179, -v174, v175, 1.0
	v_fmac_f32_e32 v175, v179, v175
	v_mul_f32_e32 v177, v176, v175
	v_fma_f32 v178, -v174, v177, v176
	v_fmac_f32_e32 v177, v178, v175
	v_fma_f32 v174, -v174, v177, v176
	v_div_fmas_f32 v174, v174, v175, v177
	v_div_fixup_f32 v181, v174, v232, 1.0
	v_div_scale_f32 v174, s[18:19], v231, v231, 1.0
	v_rcp_f32_e32 v175, v174
	v_div_scale_f32 v176, vcc, 1.0, v231, 1.0
	v_fma_f32 v179, -v174, v175, 1.0
	v_fmac_f32_e32 v175, v179, v175
	v_mul_f32_e32 v177, v176, v175
	v_fma_f32 v178, -v174, v177, v176
	v_fmac_f32_e32 v177, v178, v175
	v_fma_f32 v174, -v174, v177, v176
	v_div_fmas_f32 v174, v174, v175, v177
	v_div_fixup_f32 v180, v174, v231, 1.0
	v_pk_fma_f32 v[114:115], v[36:37], v[180:181], v[114:115]
	v_lshlrev_b32_e32 v233, 16, v233
	v_lshlrev_b32_e32 v235, 16, v235
	v_mul_f32_e32 v233, 0xbfb8aa3b, v233
	v_mul_f32_e32 v235, 0xbfb8aa3b, v235
	v_exp_f32_e32 v233, v233
	v_exp_f32_e32 v235, v235
	v_add_f32_e64 v233, v233, 1.0
	v_add_f32_e64 v235, v235, 1.0
	v_div_scale_f32 v174, s[18:19], v235, v235, 1.0
	v_rcp_f32_e32 v175, v174
	v_div_scale_f32 v176, vcc, 1.0, v235, 1.0
	v_fma_f32 v179, -v174, v175, 1.0
	v_fmac_f32_e32 v175, v179, v175
	v_mul_f32_e32 v177, v176, v175
	v_fma_f32 v178, -v174, v177, v176
	v_fmac_f32_e32 v177, v178, v175
	v_fma_f32 v174, -v174, v177, v176
	v_div_fmas_f32 v174, v174, v175, v177
	v_div_fixup_f32 v181, v174, v235, 1.0
	v_div_scale_f32 v174, s[18:19], v233, v233, 1.0
	v_rcp_f32_e32 v175, v174
	v_div_scale_f32 v176, vcc, 1.0, v233, 1.0
	v_fma_f32 v179, -v174, v175, 1.0
	v_fmac_f32_e32 v175, v179, v175
	v_mul_f32_e32 v177, v176, v175
	v_fma_f32 v178, -v174, v177, v176
	v_fmac_f32_e32 v177, v178, v175
	v_fma_f32 v174, -v174, v177, v176
	v_div_fmas_f32 v174, v174, v175, v177
	v_div_fixup_f32 v180, v174, v233, 1.0
	v_pk_fma_f32 v[112:113], v[38:39], v[180:181], v[112:113]
	v_lshlrev_b32_e32 v236, 16, v236
	v_lshlrev_b32_e32 v237, 16, v237
	v_mul_f32_e32 v236, 0xbfb8aa3b, v236
	v_mul_f32_e32 v237, 0xbfb8aa3b, v237
	v_exp_f32_e32 v236, v236
	v_exp_f32_e32 v237, v237
	v_add_f32_e64 v236, v236, 1.0
	v_add_f32_e64 v237, v237, 1.0
	v_div_scale_f32 v174, s[18:19], v237, v237, 1.0
	v_rcp_f32_e32 v175, v174
	v_div_scale_f32 v176, vcc, 1.0, v237, 1.0
	v_fma_f32 v179, -v174, v175, 1.0
	v_fmac_f32_e32 v175, v179, v175
; DI float bf2f(bfr v) { return __uint_as_float(((unsigned)v) << 16); }
; DI float sigmoidf_(float x) { return 1.f / (1.f + __expf(-x)); }
; DI void phase_merge(const Params& p, int l, unsigned char* smem) {
;     ...
; #pragma unroll
;           for (int r = 0; r < 16; ++r) {
;             const float g = bf2f(gp[(size_t)((r & 3) + 8 * (r >> 2)) * PLD]);
;             tot[mi][ni][r] += sigmoidf_(g) * acc[mi][ni][r];
	v_mul_f32_e32 v177, v176, v175
	v_fma_f32 v178, -v174, v177, v176
	v_fmac_f32_e32 v177, v178, v175
	v_fma_f32 v174, -v174, v177, v176
	v_div_fmas_f32 v174, v174, v175, v177
	v_div_fixup_f32 v181, v174, v237, 1.0
	v_div_scale_f32 v174, s[18:19], v236, v236, 1.0
	v_rcp_f32_e32 v175, v174
	v_div_scale_f32 v176, vcc, 1.0, v236, 1.0
	v_fma_f32 v179, -v174, v175, 1.0
	v_fmac_f32_e32 v175, v179, v175
	v_mul_f32_e32 v177, v176, v175
	v_fma_f32 v178, -v174, v177, v176
	v_fmac_f32_e32 v177, v178, v175
	v_fma_f32 v174, -v174, v177, v176
	v_div_fmas_f32 v174, v174, v175, v177
	v_div_fixup_f32 v180, v174, v236, 1.0
	v_pk_fma_f32 v[110:111], v[40:41], v[180:181], v[110:111]
	v_lshlrev_b32_e32 v238, 16, v238
	v_lshlrev_b32_e32 v239, 16, v239
	v_mul_f32_e32 v238, 0xbfb8aa3b, v238
	v_mul_f32_e32 v239, 0xbfb8aa3b, v239
	v_exp_f32_e32 v238, v238
	v_exp_f32_e32 v239, v239
	v_add_f32_e64 v238, v238, 1.0
	v_add_f32_e64 v239, v239, 1.0
	v_div_scale_f32 v174, s[18:19], v239, v239, 1.0
	v_rcp_f32_e32 v175, v174
	v_div_scale_f32 v176, vcc, 1.0, v239, 1.0
	v_fma_f32 v179, -v174, v175, 1.0
	v_fmac_f32_e32 v175, v179, v175
	v_mul_f32_e32 v177, v176, v175
	v_fma_f32 v178, -v174, v177, v176
	v_fmac_f32_e32 v177, v178, v175
	v_fma_f32 v174, -v174, v177, v176
	v_div_fmas_f32 v174, v174, v175, v177
	v_div_fixup_f32 v181, v174, v239, 1.0
	v_div_scale_f32 v174, s[18:19], v238, v238, 1.0
	v_rcp_f32_e32 v175, v174
	v_div_scale_f32 v176, vcc, 1.0, v238, 1.0
	v_fma_f32 v179, -v174, v175, 1.0
	v_fmac_f32_e32 v175, v179, v175
	v_mul_f32_e32 v177, v176, v175
	v_fma_f32 v178, -v174, v177, v176
	v_fmac_f32_e32 v177, v178, v175
	v_fma_f32 v174, -v174, v177, v176
	v_div_fmas_f32 v174, v174, v175, v177
	v_div_fixup_f32 v180, v174, v238, 1.0
	v_pk_fma_f32 v[108:109], v[42:43], v[180:181], v[108:109]
	v_lshlrev_b32_e32 v240, 16, v240
	v_lshlrev_b32_e32 v241, 16, v241
	v_mul_f32_e32 v240, 0xbfb8aa3b, v240
	v_mul_f32_e32 v241, 0xbfb8aa3b, v241
	v_exp_f32_e32 v240, v240
	v_exp_f32_e32 v241, v241
	v_add_f32_e64 v240, v240, 1.0
	v_add_f32_e64 v241, v241, 1.0
	v_div_scale_f32 v174, s[18:19], v241, v241, 1.0
	v_rcp_f32_e32 v175, v174
	v_div_scale_f32 v176, vcc, 1.0, v241, 1.0
	v_fma_f32 v179, -v174, v175, 1.0
	v_fmac_f32_e32 v175, v179, v175
	v_mul_f32_e32 v177, v176, v175
	v_fma_f32 v178, -v174, v177, v176
	v_fmac_f32_e32 v177, v178, v175
	v_fma_f32 v174, -v174, v177, v176
	v_div_fmas_f32 v174, v174, v175, v177
	v_div_fixup_f32 v181, v174, v241, 1.0
	v_div_scale_f32 v174, s[18:19], v240, v240, 1.0
	v_rcp_f32_e32 v175, v174
	v_div_scale_f32 v176, vcc, 1.0, v240, 1.0
	v_fma_f32 v179, -v174, v175, 1.0
	v_fmac_f32_e32 v175, v179, v175
	v_mul_f32_e32 v177, v176, v175
	v_fma_f32 v178, -v174, v177, v176
	v_fmac_f32_e32 v177, v178, v175
	v_fma_f32 v174, -v174, v177, v176
	v_div_fmas_f32 v174, v174, v175, v177
	v_div_fixup_f32 v180, v174, v240, 1.0
	v_pk_fma_f32 v[106:107], v[44:45], v[180:181], v[106:107]
	v_lshlrev_b32_e32 v242, 16, v242
	v_lshlrev_b32_e32 v244, 16, v244
	v_mul_f32_e32 v242, 0xbfb8aa3b, v242
	v_mul_f32_e32 v244, 0xbfb8aa3b, v244
	v_exp_f32_e32 v242, v242
	v_exp_f32_e32 v244, v244
	v_add_f32_e64 v242, v242, 1.0
	v_add_f32_e64 v244, v244, 1.0
	v_div_scale_f32 v174, s[18:19], v244, v244, 1.0
	v_rcp_f32_e32 v175, v174
	v_div_scale_f32 v176, vcc, 1.0, v244, 1.0
	v_fma_f32 v179, -v174, v175, 1.0
	v_fmac_f32_e32 v175, v179, v175
	v_mul_f32_e32 v177, v176, v175
	v_fma_f32 v178, -v174, v177, v176
	v_fmac_f32_e32 v177, v178, v175
	v_fma_f32 v174, -v174, v177, v176
	v_div_fmas_f32 v174, v174, v175, v177
	v_div_fixup_f32 v181, v174, v244, 1.0
	v_div_scale_f32 v174, s[18:19], v242, v242, 1.0
	v_rcp_f32_e32 v175, v174
	v_div_scale_f32 v176, vcc, 1.0, v242, 1.0
	v_fma_f32 v179, -v174, v175, 1.0
	v_fmac_f32_e32 v175, v179, v175
	v_mul_f32_e32 v177, v176, v175
	v_fma_f32 v178, -v174, v177, v176
	v_fmac_f32_e32 v177, v178, v175
	v_fma_f32 v174, -v174, v177, v176
	v_div_fmas_f32 v174, v174, v175, v177
	v_div_fixup_f32 v180, v174, v242, 1.0
	v_pk_fma_f32 v[104:105], v[46:47], v[180:181], v[104:105]
	s_waitcnt vmcnt(0)
	v_lshlrev_b32_e32 v136, 16, v136
	v_lshlrev_b32_e32 v137, 16, v137
	v_mul_f32_e32 v136, 0xbfb8aa3b, v136
	v_mul_f32_e32 v137, 0xbfb8aa3b, v137
	v_exp_f32_e32 v136, v136
	v_exp_f32_e32 v137, v137
	v_add_f32_e64 v136, v136, 1.0
	v_add_f32_e64 v137, v137, 1.0
	v_div_scale_f32 v174, s[18:19], v137, v137, 1.0
	v_rcp_f32_e32 v175, v174
	v_div_scale_f32 v176, vcc, 1.0, v137, 1.0
	v_fma_f32 v179, -v174, v175, 1.0
	v_fmac_f32_e32 v175, v179, v175
	v_mul_f32_e32 v177, v176, v175
	v_fma_f32 v178, -v174, v177, v176
	v_fmac_f32_e32 v177, v178, v175
	v_fma_f32 v174, -v174, v177, v176
	v_div_fmas_f32 v174, v174, v175, v177
	v_div_fixup_f32 v181, v174, v137, 1.0
	v_div_scale_f32 v174, s[18:19], v136, v136, 1.0
	v_rcp_f32_e32 v175, v174
	v_div_scale_f32 v176, vcc, 1.0, v136, 1.0
	v_fma_f32 v179, -v174, v175, 1.0
	v_fmac_f32_e32 v175, v179, v175
	v_mul_f32_e32 v177, v176, v175
	v_fma_f32 v178, -v174, v177, v176
	v_fmac_f32_e32 v177, v178, v175
	v_fma_f32 v174, -v174, v177, v176
	v_div_fmas_f32 v174, v174, v175, v177
	v_div_fixup_f32 v180, v174, v136, 1.0
	v_pk_fma_f32 v[102:103], v[16:17], v[180:181], v[102:103]
	v_lshlrev_b32_e32 v138, 16, v138
	v_lshlrev_b32_e32 v139, 16, v139
	v_mul_f32_e32 v138, 0xbfb8aa3b, v138
	v_mul_f32_e32 v139, 0xbfb8aa3b, v139
	v_exp_f32_e32 v138, v138
	v_exp_f32_e32 v139, v139
	v_add_f32_e64 v138, v138, 1.0
	v_add_f32_e64 v139, v139, 1.0
	v_div_scale_f32 v174, s[18:19], v139, v139, 1.0
	v_rcp_f32_e32 v175, v174
	v_div_scale_f32 v176, vcc, 1.0, v139, 1.0
	v_fma_f32 v179, -v174, v175, 1.0
	v_fmac_f32_e32 v175, v179, v175
	v_mul_f32_e32 v177, v176, v175
	v_fma_f32 v178, -v174, v177, v176
; DI float bf2f(bfr v) { return __uint_as_float(((unsigned)v) << 16); }
; DI float sigmoidf_(float x) { return 1.f / (1.f + __expf(-x)); }
; DI void phase_merge(const Params& p, int l, unsigned char* smem) {
;     ...
; #pragma unroll
;           for (int r = 0; r < 16; ++r) {
;             const float g = bf2f(gp[(size_t)((r & 3) + 8 * (r >> 2)) * PLD]);
;             tot[mi][ni][r] += sigmoidf_(g) * acc[mi][ni][r];
	v_fmac_f32_e32 v177, v178, v175
	v_fma_f32 v174, -v174, v177, v176
	v_div_fmas_f32 v174, v174, v175, v177
	v_div_fixup_f32 v181, v174, v139, 1.0
	v_div_scale_f32 v174, s[18:19], v138, v138, 1.0
	v_rcp_f32_e32 v175, v174
	v_div_scale_f32 v176, vcc, 1.0, v138, 1.0
	v_fma_f32 v179, -v174, v175, 1.0
	v_fmac_f32_e32 v175, v179, v175
	v_mul_f32_e32 v177, v176, v175
	v_fma_f32 v178, -v174, v177, v176
	v_fmac_f32_e32 v177, v178, v175
	v_fma_f32 v174, -v174, v177, v176
	v_div_fmas_f32 v174, v174, v175, v177
	v_div_fixup_f32 v180, v174, v138, 1.0
	v_pk_fma_f32 v[100:101], v[18:19], v[180:181], v[100:101]
	v_lshlrev_b32_e32 v140, 16, v140
	v_lshlrev_b32_e32 v141, 16, v141
	v_mul_f32_e32 v140, 0xbfb8aa3b, v140
	v_mul_f32_e32 v141, 0xbfb8aa3b, v141
	v_exp_f32_e32 v140, v140
	v_exp_f32_e32 v141, v141
	v_add_f32_e64 v140, v140, 1.0
	v_add_f32_e64 v141, v141, 1.0
	v_div_scale_f32 v174, s[18:19], v141, v141, 1.0
	v_rcp_f32_e32 v175, v174
	v_div_scale_f32 v176, vcc, 1.0, v141, 1.0
	v_fma_f32 v179, -v174, v175, 1.0
	v_fmac_f32_e32 v175, v179, v175
	v_mul_f32_e32 v177, v176, v175
	v_fma_f32 v178, -v174, v177, v176
	v_fmac_f32_e32 v177, v178, v175
	v_fma_f32 v174, -v174, v177, v176
	v_div_fmas_f32 v174, v174, v175, v177
	v_div_fixup_f32 v181, v174, v141, 1.0
	v_div_scale_f32 v174, s[18:19], v140, v140, 1.0
	v_rcp_f32_e32 v175, v174
	v_div_scale_f32 v176, vcc, 1.0, v140, 1.0
	v_fma_f32 v179, -v174, v175, 1.0
	v_fmac_f32_e32 v175, v179, v175
	v_mul_f32_e32 v177, v176, v175
	v_fma_f32 v178, -v174, v177, v176
	v_fmac_f32_e32 v177, v178, v175
	v_fma_f32 v174, -v174, v177, v176
	v_div_fmas_f32 v174, v174, v175, v177
	v_div_fixup_f32 v180, v174, v140, 1.0
	v_pk_fma_f32 v[98:99], v[20:21], v[180:181], v[98:99]
	v_lshlrev_b32_e32 v142, 16, v142
	v_lshlrev_b32_e32 v143, 16, v143
	v_mul_f32_e32 v142, 0xbfb8aa3b, v142
	v_mul_f32_e32 v143, 0xbfb8aa3b, v143
	v_exp_f32_e32 v142, v142
	v_exp_f32_e32 v143, v143
	v_add_f32_e64 v142, v142, 1.0
	v_add_f32_e64 v143, v143, 1.0
	v_div_scale_f32 v174, s[18:19], v143, v143, 1.0
	v_rcp_f32_e32 v175, v174
	v_div_scale_f32 v176, vcc, 1.0, v143, 1.0
	v_fma_f32 v179, -v174, v175, 1.0
	v_fmac_f32_e32 v175, v179, v175
	v_mul_f32_e32 v177, v176, v175
	v_fma_f32 v178, -v174, v177, v176
	v_fmac_f32_e32 v177, v178, v175
	v_fma_f32 v174, -v174, v177, v176
	v_div_fmas_f32 v174, v174, v175, v177
	v_div_fixup_f32 v181, v174, v143, 1.0
	v_div_scale_f32 v174, s[18:19], v142, v142, 1.0
	v_rcp_f32_e32 v175, v174
	v_div_scale_f32 v176, vcc, 1.0, v142, 1.0
	v_fma_f32 v179, -v174, v175, 1.0
	v_fmac_f32_e32 v175, v179, v175
	v_mul_f32_e32 v177, v176, v175
	v_fma_f32 v178, -v174, v177, v176
	v_fmac_f32_e32 v177, v178, v175
	v_fma_f32 v174, -v174, v177, v176
	v_div_fmas_f32 v174, v174, v175, v177
	v_div_fixup_f32 v180, v174, v142, 1.0
	v_pk_fma_f32 v[94:95], v[22:23], v[180:181], v[94:95]
	v_lshlrev_b32_e32 v144, 16, v144
	v_lshlrev_b32_e32 v145, 16, v145
	v_mul_f32_e32 v144, 0xbfb8aa3b, v144
	v_mul_f32_e32 v145, 0xbfb8aa3b, v145
	v_exp_f32_e32 v144, v144
	v_exp_f32_e32 v145, v145
	v_add_f32_e64 v144, v144, 1.0
	v_add_f32_e64 v145, v145, 1.0
	v_div_scale_f32 v174, s[18:19], v145, v145, 1.0
	v_rcp_f32_e32 v175, v174
	v_div_scale_f32 v176, vcc, 1.0, v145, 1.0
	v_fma_f32 v179, -v174, v175, 1.0
	v_fmac_f32_e32 v175, v179, v175
	v_mul_f32_e32 v177, v176, v175
	v_fma_f32 v178, -v174, v177, v176
	v_fmac_f32_e32 v177, v178, v175
	v_fma_f32 v174, -v174, v177, v176
	v_div_fmas_f32 v174, v174, v175, v177
	v_div_fixup_f32 v181, v174, v145, 1.0
	v_div_scale_f32 v174, s[18:19], v144, v144, 1.0
	v_rcp_f32_e32 v175, v174
	v_div_scale_f32 v176, vcc, 1.0, v144, 1.0
	v_fma_f32 v179, -v174, v175, 1.0
	v_fmac_f32_e32 v175, v179, v175
	v_mul_f32_e32 v177, v176, v175
	v_fma_f32 v178, -v174, v177, v176
	v_fmac_f32_e32 v177, v178, v175
	v_fma_f32 v174, -v174, v177, v176
	v_div_fmas_f32 v174, v174, v175, v177
	v_div_fixup_f32 v180, v174, v144, 1.0
	v_pk_fma_f32 v[92:93], v[24:25], v[180:181], v[92:93]
	v_lshlrev_b32_e32 v146, 16, v146
	v_lshlrev_b32_e32 v147, 16, v147
	v_mul_f32_e32 v146, 0xbfb8aa3b, v146
	v_mul_f32_e32 v147, 0xbfb8aa3b, v147
	v_exp_f32_e32 v146, v146
	v_exp_f32_e32 v147, v147
	v_add_f32_e64 v146, v146, 1.0
	v_add_f32_e64 v147, v147, 1.0
	v_div_scale_f32 v174, s[18:19], v147, v147, 1.0
	v_rcp_f32_e32 v175, v174
	v_div_scale_f32 v176, vcc, 1.0, v147, 1.0
	v_fma_f32 v179, -v174, v175, 1.0
	v_fmac_f32_e32 v175, v179, v175
	v_mul_f32_e32 v177, v176, v175
	v_fma_f32 v178, -v174, v177, v176
	v_fmac_f32_e32 v177, v178, v175
	v_fma_f32 v174, -v174, v177, v176
	v_div_fmas_f32 v174, v174, v175, v177
	v_div_fixup_f32 v181, v174, v147, 1.0
	v_div_scale_f32 v174, s[18:19], v146, v146, 1.0
	v_rcp_f32_e32 v175, v174
	v_div_scale_f32 v176, vcc, 1.0, v146, 1.0
	v_fma_f32 v179, -v174, v175, 1.0
	v_fmac_f32_e32 v175, v179, v175
	v_mul_f32_e32 v177, v176, v175
	v_fma_f32 v178, -v174, v177, v176
	v_fmac_f32_e32 v177, v178, v175
	v_fma_f32 v174, -v174, v177, v176
	v_div_fmas_f32 v174, v174, v175, v177
	v_div_fixup_f32 v180, v174, v146, 1.0
	v_pk_fma_f32 v[90:91], v[26:27], v[180:181], v[90:91]
	v_lshlrev_b32_e32 v148, 16, v148
	v_lshlrev_b32_e32 v149, 16, v149
	v_mul_f32_e32 v148, 0xbfb8aa3b, v148
	v_mul_f32_e32 v149, 0xbfb8aa3b, v149
	v_exp_f32_e32 v148, v148
	v_exp_f32_e32 v149, v149
	v_add_f32_e64 v148, v148, 1.0
	v_add_f32_e64 v149, v149, 1.0
	v_div_scale_f32 v174, s[18:19], v149, v149, 1.0
	v_rcp_f32_e32 v175, v174
	v_div_scale_f32 v176, vcc, 1.0, v149, 1.0
	v_fma_f32 v179, -v174, v175, 1.0
	v_fmac_f32_e32 v175, v179, v175
	v_mul_f32_e32 v177, v176, v175
	v_fma_f32 v178, -v174, v177, v176
	v_fmac_f32_e32 v177, v178, v175
	v_fma_f32 v174, -v174, v177, v176
	v_div_fmas_f32 v174, v174, v175, v177
; DI float bf2f(bfr v) { return __uint_as_float(((unsigned)v) << 16); }
; DI float sigmoidf_(float x) { return 1.f / (1.f + __expf(-x)); }
; DI void phase_merge(const Params& p, int l, unsigned char* smem) {
;     ...
; #pragma unroll
;           for (int r = 0; r < 16; ++r) {
;             const float g = bf2f(gp[(size_t)((r & 3) + 8 * (r >> 2)) * PLD]);
;             tot[mi][ni][r] += sigmoidf_(g) * acc[mi][ni][r];
	v_div_fixup_f32 v181, v174, v149, 1.0
	v_div_scale_f32 v174, s[18:19], v148, v148, 1.0
	v_rcp_f32_e32 v175, v174
	v_div_scale_f32 v176, vcc, 1.0, v148, 1.0
	v_fma_f32 v179, -v174, v175, 1.0
	v_fmac_f32_e32 v175, v179, v175
	v_mul_f32_e32 v177, v176, v175
	v_fma_f32 v178, -v174, v177, v176
	v_fmac_f32_e32 v177, v178, v175
	v_fma_f32 v174, -v174, v177, v176
	v_div_fmas_f32 v174, v174, v175, v177
	v_div_fixup_f32 v180, v174, v148, 1.0
	v_pk_fma_f32 v[88:89], v[28:29], v[180:181], v[88:89]
	v_lshlrev_b32_e32 v150, 16, v150
	v_lshlrev_b32_e32 v151, 16, v151
	v_mul_f32_e32 v150, 0xbfb8aa3b, v150
	v_mul_f32_e32 v151, 0xbfb8aa3b, v151
	v_exp_f32_e32 v150, v150
	v_exp_f32_e32 v151, v151
	v_add_f32_e64 v150, v150, 1.0
	v_add_f32_e64 v151, v151, 1.0
	v_div_scale_f32 v174, s[18:19], v151, v151, 1.0
	v_rcp_f32_e32 v175, v174
	v_div_scale_f32 v176, vcc, 1.0, v151, 1.0
	v_fma_f32 v179, -v174, v175, 1.0
	v_fmac_f32_e32 v175, v179, v175
	v_mul_f32_e32 v177, v176, v175
	v_fma_f32 v178, -v174, v177, v176
	v_fmac_f32_e32 v177, v178, v175
	v_fma_f32 v174, -v174, v177, v176
	v_div_fmas_f32 v174, v174, v175, v177
	v_div_fixup_f32 v181, v174, v151, 1.0
	v_div_scale_f32 v174, s[18:19], v150, v150, 1.0
	v_rcp_f32_e32 v175, v174
	v_div_scale_f32 v176, vcc, 1.0, v150, 1.0
	v_fma_f32 v179, -v174, v175, 1.0
	v_fmac_f32_e32 v175, v179, v175
	v_mul_f32_e32 v177, v176, v175
	v_fma_f32 v178, -v174, v177, v176
	v_fmac_f32_e32 v177, v178, v175
	v_fma_f32 v174, -v174, v177, v176
	v_div_fmas_f32 v174, v174, v175, v177
	v_div_fixup_f32 v180, v174, v150, 1.0
	v_pk_fma_f32 v[86:87], v[30:31], v[180:181], v[86:87]
	v_lshlrev_b32_e32 v158, 16, v158
	v_lshlrev_b32_e32 v159, 16, v159
	v_mul_f32_e32 v158, 0xbfb8aa3b, v158
	v_mul_f32_e32 v159, 0xbfb8aa3b, v159
	v_exp_f32_e32 v158, v158
	v_exp_f32_e32 v159, v159
	v_add_f32_e64 v158, v158, 1.0
	v_add_f32_e64 v159, v159, 1.0
	v_div_scale_f32 v174, s[18:19], v159, v159, 1.0
	v_rcp_f32_e32 v175, v174
	v_div_scale_f32 v176, vcc, 1.0, v159, 1.0
	v_fma_f32 v179, -v174, v175, 1.0
	v_fmac_f32_e32 v175, v179, v175
	v_mul_f32_e32 v177, v176, v175
	v_fma_f32 v178, -v174, v177, v176
	v_fmac_f32_e32 v177, v178, v175
	v_fma_f32 v174, -v174, v177, v176
	v_div_fmas_f32 v174, v174, v175, v177
	v_div_fixup_f32 v181, v174, v159, 1.0
	v_div_scale_f32 v174, s[18:19], v158, v158, 1.0
	v_rcp_f32_e32 v175, v174
	v_div_scale_f32 v176, vcc, 1.0, v158, 1.0
	v_fma_f32 v179, -v174, v175, 1.0
	v_fmac_f32_e32 v175, v179, v175
	v_mul_f32_e32 v177, v176, v175
	v_fma_f32 v178, -v174, v177, v176
	v_fmac_f32_e32 v177, v178, v175
	v_fma_f32 v174, -v174, v177, v176
	v_div_fmas_f32 v174, v174, v175, v177
	v_div_fixup_f32 v180, v174, v158, 1.0
	v_pk_fma_f32 v[84:85], v[0:1], v[180:181], v[84:85]
	v_lshlrev_b32_e32 v160, 16, v160
	v_lshlrev_b32_e32 v161, 16, v161
	v_mul_f32_e32 v160, 0xbfb8aa3b, v160
	v_mul_f32_e32 v161, 0xbfb8aa3b, v161
	v_exp_f32_e32 v160, v160
	v_exp_f32_e32 v161, v161
	v_add_f32_e64 v160, v160, 1.0
	v_add_f32_e64 v161, v161, 1.0
	v_div_scale_f32 v174, s[18:19], v161, v161, 1.0
	v_rcp_f32_e32 v175, v174
	v_div_scale_f32 v176, vcc, 1.0, v161, 1.0
	v_fma_f32 v179, -v174, v175, 1.0
	v_fmac_f32_e32 v175, v179, v175
	v_mul_f32_e32 v177, v176, v175
	v_fma_f32 v178, -v174, v177, v176
	v_fmac_f32_e32 v177, v178, v175
	v_fma_f32 v174, -v174, v177, v176
	v_div_fmas_f32 v174, v174, v175, v177
	v_div_fixup_f32 v181, v174, v161, 1.0
	v_div_scale_f32 v174, s[18:19], v160, v160, 1.0
	v_rcp_f32_e32 v175, v174
	v_div_scale_f32 v176, vcc, 1.0, v160, 1.0
	v_fma_f32 v179, -v174, v175, 1.0
	v_fmac_f32_e32 v175, v179, v175
	v_mul_f32_e32 v177, v176, v175
	v_fma_f32 v178, -v174, v177, v176
	v_fmac_f32_e32 v177, v178, v175
	v_fma_f32 v174, -v174, v177, v176
	v_div_fmas_f32 v174, v174, v175, v177
	v_div_fixup_f32 v180, v174, v160, 1.0
	v_pk_fma_f32 v[82:83], v[2:3], v[180:181], v[82:83]
	v_lshlrev_b32_e32 v162, 16, v162
	v_lshlrev_b32_e32 v163, 16, v163
	v_mul_f32_e32 v162, 0xbfb8aa3b, v162
	v_mul_f32_e32 v163, 0xbfb8aa3b, v163
	v_exp_f32_e32 v162, v162
	v_exp_f32_e32 v163, v163
	v_add_f32_e64 v162, v162, 1.0
	v_add_f32_e64 v163, v163, 1.0
	v_div_scale_f32 v174, s[18:19], v163, v163, 1.0
	v_rcp_f32_e32 v175, v174
	v_div_scale_f32 v176, vcc, 1.0, v163, 1.0
	v_fma_f32 v179, -v174, v175, 1.0
	v_fmac_f32_e32 v175, v179, v175
	v_mul_f32_e32 v177, v176, v175
	v_fma_f32 v178, -v174, v177, v176
	v_fmac_f32_e32 v177, v178, v175
	v_fma_f32 v174, -v174, v177, v176
	v_div_fmas_f32 v174, v174, v175, v177
	v_div_fixup_f32 v181, v174, v163, 1.0
	v_div_scale_f32 v174, s[18:19], v162, v162, 1.0
	v_rcp_f32_e32 v175, v174
	v_div_scale_f32 v176, vcc, 1.0, v162, 1.0
	v_fma_f32 v179, -v174, v175, 1.0
	v_fmac_f32_e32 v175, v179, v175
	v_mul_f32_e32 v177, v176, v175
	v_fma_f32 v178, -v174, v177, v176
	v_fmac_f32_e32 v177, v178, v175
	v_fma_f32 v174, -v174, v177, v176
	v_div_fmas_f32 v174, v174, v175, v177
	v_div_fixup_f32 v180, v174, v162, 1.0
	v_pk_fma_f32 v[80:81], v[4:5], v[180:181], v[80:81]
	v_lshlrev_b32_e32 v164, 16, v164
	v_lshlrev_b32_e32 v165, 16, v165
	v_mul_f32_e32 v164, 0xbfb8aa3b, v164
	v_mul_f32_e32 v165, 0xbfb8aa3b, v165
	v_exp_f32_e32 v164, v164
	v_exp_f32_e32 v165, v165
	v_add_f32_e64 v164, v164, 1.0
	v_add_f32_e64 v165, v165, 1.0
	v_div_scale_f32 v174, s[18:19], v165, v165, 1.0
	v_rcp_f32_e32 v175, v174
	v_div_scale_f32 v176, vcc, 1.0, v165, 1.0
	v_fma_f32 v179, -v174, v175, 1.0
	v_fmac_f32_e32 v175, v179, v175
	v_mul_f32_e32 v177, v176, v175
	v_fma_f32 v178, -v174, v177, v176
	v_fmac_f32_e32 v177, v178, v175
	v_fma_f32 v174, -v174, v177, v176
	v_div_fmas_f32 v174, v174, v175, v177
	v_div_fixup_f32 v181, v174, v165, 1.0
	v_div_scale_f32 v174, s[18:19], v164, v164, 1.0
; DI float bf2f(bfr v) { return __uint_as_float(((unsigned)v) << 16); }
; DI float sigmoidf_(float x) { return 1.f / (1.f + __expf(-x)); }
; DI f32x16 zero16() { f32x16 z; for (int i = 0; i < 16; ++i) z[i] = 0.f; return z; }
; DI void phase_merge(const Params& p, int l, unsigned char* smem) {
;     ...
;     for (int nb = 0; nb < 4; ++nb) {
;       f32x16 acc[2][2];
;       for (int i = 0; i < 2; ++i) for (int j = 0; j < 2; ++j) acc[i][j] = zero16();
;       gemm_main<2>(YS + (size_t)m0 * DM + nb * 512, DM, (const bfr*)(WS_ + O_WBR) + ((size_t)(l * 4 + nb) * 2048 + n0) * 512, 512, 512, acc, sA, sB);
; #pragma unroll
;       for (int mi = 0; mi < 2; ++mi)
; #pragma unroll
;         for (int ni = 0; ni < 2; ++ni) {
;           int rbo = m0 + wm * 64 + mi * 32 + 4 * h;
;           asm volatile("" : "+v"(rbo));
;           const bfr* gp = P + (size_t)rbo * PLD + C_GATE + nb * 2048 + n0 + wn * 64 + ni * 32 + l31;
; #pragma unroll
;           for (int r = 0; r < 16; ++r) {
;             const float g = bf2f(gp[(size_t)((r & 3) + 8 * (r >> 2)) * PLD]);
;             tot[mi][ni][r] += sigmoidf_(g) * acc[mi][ni][r];
;           }
;           __builtin_amdgcn_sched_barrier(0);
;         }
	v_rcp_f32_e32 v175, v174
	v_div_scale_f32 v176, vcc, 1.0, v164, 1.0
	v_fma_f32 v179, -v174, v175, 1.0
	v_fmac_f32_e32 v175, v179, v175
	v_mul_f32_e32 v177, v176, v175
	v_fma_f32 v178, -v174, v177, v176
	v_fmac_f32_e32 v177, v178, v175
	v_fma_f32 v174, -v174, v177, v176
	v_div_fmas_f32 v174, v174, v175, v177
	v_div_fixup_f32 v180, v174, v164, 1.0
	v_pk_fma_f32 v[78:79], v[6:7], v[180:181], v[78:79]
	v_lshlrev_b32_e32 v166, 16, v166
	v_lshlrev_b32_e32 v167, 16, v167
	v_mul_f32_e32 v166, 0xbfb8aa3b, v166
	v_mul_f32_e32 v167, 0xbfb8aa3b, v167
	v_exp_f32_e32 v166, v166
	v_exp_f32_e32 v167, v167
	v_add_f32_e64 v166, v166, 1.0
	v_add_f32_e64 v167, v167, 1.0
	v_div_scale_f32 v174, s[18:19], v167, v167, 1.0
	v_rcp_f32_e32 v175, v174
	v_div_scale_f32 v176, vcc, 1.0, v167, 1.0
	v_fma_f32 v179, -v174, v175, 1.0
	v_fmac_f32_e32 v175, v179, v175
	v_mul_f32_e32 v177, v176, v175
	v_fma_f32 v178, -v174, v177, v176
	v_fmac_f32_e32 v177, v178, v175
	v_fma_f32 v174, -v174, v177, v176
	v_div_fmas_f32 v174, v174, v175, v177
	v_div_fixup_f32 v181, v174, v167, 1.0
	v_div_scale_f32 v174, s[18:19], v166, v166, 1.0
	v_rcp_f32_e32 v175, v174
	v_div_scale_f32 v176, vcc, 1.0, v166, 1.0
	v_fma_f32 v179, -v174, v175, 1.0
	v_fmac_f32_e32 v175, v179, v175
	v_mul_f32_e32 v177, v176, v175
	v_fma_f32 v178, -v174, v177, v176
	v_fmac_f32_e32 v177, v178, v175
	v_fma_f32 v174, -v174, v177, v176
	v_div_fmas_f32 v174, v174, v175, v177
	v_div_fixup_f32 v180, v174, v166, 1.0
	v_pk_fma_f32 v[76:77], v[8:9], v[180:181], v[76:77]
	v_lshlrev_b32_e32 v168, 16, v168
	v_lshlrev_b32_e32 v169, 16, v169
	v_mul_f32_e32 v168, 0xbfb8aa3b, v168
	v_mul_f32_e32 v169, 0xbfb8aa3b, v169
	v_exp_f32_e32 v168, v168
	v_exp_f32_e32 v169, v169
	v_add_f32_e64 v168, v168, 1.0
	v_add_f32_e64 v169, v169, 1.0
	v_div_scale_f32 v174, s[18:19], v169, v169, 1.0
	v_rcp_f32_e32 v175, v174
	v_div_scale_f32 v176, vcc, 1.0, v169, 1.0
	v_fma_f32 v179, -v174, v175, 1.0
	v_fmac_f32_e32 v175, v179, v175
	v_mul_f32_e32 v177, v176, v175
	v_fma_f32 v178, -v174, v177, v176
	v_fmac_f32_e32 v177, v178, v175
	v_fma_f32 v174, -v174, v177, v176
	v_div_fmas_f32 v174, v174, v175, v177
	v_div_fixup_f32 v181, v174, v169, 1.0
	v_div_scale_f32 v174, s[18:19], v168, v168, 1.0
	v_rcp_f32_e32 v175, v174
	v_div_scale_f32 v176, vcc, 1.0, v168, 1.0
	v_fma_f32 v179, -v174, v175, 1.0
	v_fmac_f32_e32 v175, v179, v175
	v_mul_f32_e32 v177, v176, v175
	v_fma_f32 v178, -v174, v177, v176
	v_fmac_f32_e32 v177, v178, v175
	v_fma_f32 v174, -v174, v177, v176
	v_div_fmas_f32 v174, v174, v175, v177
	v_div_fixup_f32 v180, v174, v168, 1.0
	v_pk_fma_f32 v[74:75], v[10:11], v[180:181], v[74:75]
	v_lshlrev_b32_e32 v170, 16, v170
	v_lshlrev_b32_e32 v171, 16, v171
	v_mul_f32_e32 v170, 0xbfb8aa3b, v170
	v_mul_f32_e32 v171, 0xbfb8aa3b, v171
	v_exp_f32_e32 v170, v170
	v_exp_f32_e32 v171, v171
	v_add_f32_e64 v170, v170, 1.0
	v_add_f32_e64 v171, v171, 1.0
	v_div_scale_f32 v174, s[18:19], v171, v171, 1.0
	v_rcp_f32_e32 v175, v174
	v_div_scale_f32 v176, vcc, 1.0, v171, 1.0
	v_fma_f32 v179, -v174, v175, 1.0
	v_fmac_f32_e32 v175, v179, v175
	v_mul_f32_e32 v177, v176, v175
	v_fma_f32 v178, -v174, v177, v176
	v_fmac_f32_e32 v177, v178, v175
	v_fma_f32 v174, -v174, v177, v176
	v_div_fmas_f32 v174, v174, v175, v177
	v_div_fixup_f32 v181, v174, v171, 1.0
	v_div_scale_f32 v174, s[18:19], v170, v170, 1.0
	v_rcp_f32_e32 v175, v174
	v_div_scale_f32 v176, vcc, 1.0, v170, 1.0
	v_fma_f32 v179, -v174, v175, 1.0
	v_fmac_f32_e32 v175, v179, v175
	v_mul_f32_e32 v177, v176, v175
	v_fma_f32 v178, -v174, v177, v176
	v_fmac_f32_e32 v177, v178, v175
	v_fma_f32 v174, -v174, v177, v176
	v_div_fmas_f32 v174, v174, v175, v177
	v_div_fixup_f32 v180, v174, v170, 1.0
	v_pk_fma_f32 v[70:71], v[12:13], v[180:181], v[70:71]
	v_lshlrev_b32_e32 v172, 16, v172
	v_lshlrev_b32_e32 v173, 16, v173
	v_mul_f32_e32 v172, 0xbfb8aa3b, v172
	v_mul_f32_e32 v173, 0xbfb8aa3b, v173
	v_exp_f32_e32 v172, v172
	v_exp_f32_e32 v173, v173
	v_add_f32_e64 v172, v172, 1.0
	v_add_f32_e64 v173, v173, 1.0
	v_div_scale_f32 v174, s[18:19], v173, v173, 1.0
	v_rcp_f32_e32 v175, v174
	v_div_scale_f32 v176, vcc, 1.0, v173, 1.0
	v_fma_f32 v179, -v174, v175, 1.0
	v_fmac_f32_e32 v175, v179, v175
	v_mul_f32_e32 v177, v176, v175
	v_fma_f32 v178, -v174, v177, v176
	v_fmac_f32_e32 v177, v178, v175
	v_fma_f32 v174, -v174, v177, v176
	v_div_fmas_f32 v174, v174, v175, v177
	v_div_fixup_f32 v181, v174, v173, 1.0
	v_div_scale_f32 v174, s[18:19], v172, v172, 1.0
	v_rcp_f32_e32 v175, v174
	v_div_scale_f32 v176, vcc, 1.0, v172, 1.0
	v_fma_f32 v179, -v174, v175, 1.0
	v_fmac_f32_e32 v175, v179, v175
	v_mul_f32_e32 v177, v176, v175
	v_fma_f32 v178, -v174, v177, v176
	v_fmac_f32_e32 v177, v178, v175
	v_fma_f32 v174, -v174, v177, v176
	v_div_fmas_f32 v174, v174, v175, v177
	v_div_fixup_f32 v180, v174, v172, 1.0
	v_pk_fma_f32 v[68:69], v[14:15], v[180:181], v[68:69]
	s_add_i32 s37, s37, 1
	s_add_u32 s10, s10, 0x200000
	s_addc_u32 s11, s11, 0
	s_add_u32 s14, s14, 0x400
	s_addc_u32 s15, s15, 0
	s_cmp_eq_u32 s37, 4
	s_cbranch_scc0 .LBB0_560
; DI bfr f2bf(float a) { return (bfr)(pk2(a, 0.f) & 0xffffu); }
; DI int crow(int r, int h) { return (r & 3) + 8 * (r >> 2) + 4 * h; }
; DI void phase_merge(const Params& p, int l, unsigned char* smem) {
;     ...
; #pragma unroll
;     for (int mi = 0; mi < 2; ++mi)
; #pragma unroll
;       for (int ni = 0; ni < 2; ++ni) {
;         const int col = n0 + wn * 64 + ni * 32 + l31, rb = m0 + wm * 64 + mi * 32;
; #pragma unroll
;         for (int r = 0; r < 16; ++r) Y[(size_t)(rb + crow(r, h)) * DM + col] = f2bf(tot[mi][ni][r]);
	v_or_b32_e32 v0, s8, v153
	v_ashrrev_i32_e32 v1, 31, v0
	v_ashrrev_i32_e32 v73, 31, v72
	v_lshl_add_u64 v[0:1], v[0:1], 1, s[6:7]
	v_lshlrev_b64 v[2:3], 12, v[72:73]
	v_cvt_pk_bf16_f32 v4, v134, s0
	v_lshl_add_u64 v[2:3], v[0:1], 0, v[2:3]
	flat_store_short v[2:3], v4
	v_or_b32_e32 v4, 1, v72
	v_ashrrev_i32_e32 v5, 31, v4
	v_lshlrev_b64 v[4:5], 12, v[4:5]
	v_cvt_pk_bf16_f32 v6, v135, s0
	v_lshl_add_u64 v[4:5], v[0:1], 0, v[4:5]
	flat_store_short v[4:5], v6
	v_or_b32_e32 v6, 2, v72
	v_ashrrev_i32_e32 v7, 31, v6
	v_lshlrev_b64 v[6:7], 12, v[6:7]
	v_cvt_pk_bf16_f32 v8, v132, s0
	v_lshl_add_u64 v[6:7], v[0:1], 0, v[6:7]
	flat_store_short v[6:7], v8
	v_or_b32_e32 v8, 3, v72
	v_ashrrev_i32_e32 v9, 31, v8
	v_lshlrev_b64 v[8:9], 12, v[8:9]
	v_cvt_pk_bf16_f32 v10, v133, s0
	v_lshl_add_u64 v[8:9], v[0:1], 0, v[8:9]
	flat_store_short v[8:9], v10
	v_or_b32_e32 v10, 8, v72
	v_ashrrev_i32_e32 v11, 31, v10
	v_lshlrev_b64 v[10:11], 12, v[10:11]
	v_cvt_pk_bf16_f32 v12, v130, s0
	v_lshl_add_u64 v[10:11], v[0:1], 0, v[10:11]
	flat_store_short v[10:11], v12
	v_or_b32_e32 v12, 9, v72
	v_ashrrev_i32_e32 v13, 31, v12
	v_lshlrev_b64 v[12:13], 12, v[12:13]
	v_cvt_pk_bf16_f32 v14, v131, s0
	v_lshl_add_u64 v[12:13], v[0:1], 0, v[12:13]
	flat_store_short v[12:13], v14
	v_or_b32_e32 v14, 10, v72
	v_ashrrev_i32_e32 v15, 31, v14
	v_lshlrev_b64 v[14:15], 12, v[14:15]
	v_cvt_pk_bf16_f32 v16, v128, s0
	v_lshl_add_u64 v[14:15], v[0:1], 0, v[14:15]
	flat_store_short v[14:15], v16
	v_or_b32_e32 v16, 11, v72
	v_ashrrev_i32_e32 v17, 31, v16
	v_lshlrev_b64 v[16:17], 12, v[16:17]
	v_cvt_pk_bf16_f32 v18, v129, s0
	v_lshl_add_u64 v[16:17], v[0:1], 0, v[16:17]
	flat_store_short v[16:17], v18
	v_or_b32_e32 v18, 16, v72
	v_ashrrev_i32_e32 v19, 31, v18
	v_lshlrev_b64 v[18:19], 12, v[18:19]
	v_cvt_pk_bf16_f32 v20, v126, s0
	v_lshl_add_u64 v[18:19], v[0:1], 0, v[18:19]
	flat_store_short v[18:19], v20
	v_or_b32_e32 v20, 17, v72
	v_ashrrev_i32_e32 v21, 31, v20
	v_lshlrev_b64 v[20:21], 12, v[20:21]
	v_cvt_pk_bf16_f32 v22, v127, s0
	v_lshl_add_u64 v[20:21], v[0:1], 0, v[20:21]
	flat_store_short v[20:21], v22
	v_or_b32_e32 v22, 18, v72
	v_ashrrev_i32_e32 v23, 31, v22
	v_lshlrev_b64 v[22:23], 12, v[22:23]
	v_cvt_pk_bf16_f32 v24, v124, s0
	v_lshl_add_u64 v[22:23], v[0:1], 0, v[22:23]
	flat_store_short v[22:23], v24
	v_or_b32_e32 v24, 19, v72
	v_ashrrev_i32_e32 v25, 31, v24
	v_lshlrev_b64 v[24:25], 12, v[24:25]
	v_cvt_pk_bf16_f32 v26, v125, s0
	v_lshl_add_u64 v[24:25], v[0:1], 0, v[24:25]
	flat_store_short v[24:25], v26
	v_or_b32_e32 v26, 24, v72
	v_ashrrev_i32_e32 v27, 31, v26
	v_lshlrev_b64 v[26:27], 12, v[26:27]
	v_cvt_pk_bf16_f32 v28, v122, s0
	v_lshl_add_u64 v[26:27], v[0:1], 0, v[26:27]
	flat_store_short v[26:27], v28
	v_or_b32_e32 v28, 25, v72
	v_ashrrev_i32_e32 v29, 31, v28
	v_lshlrev_b64 v[28:29], 12, v[28:29]
	v_cvt_pk_bf16_f32 v30, v123, s0
	v_lshl_add_u64 v[28:29], v[0:1], 0, v[28:29]
	flat_store_short v[28:29], v30
	v_or_b32_e32 v30, 26, v72
	v_ashrrev_i32_e32 v31, 31, v30
	v_lshlrev_b64 v[30:31], 12, v[30:31]
	v_cvt_pk_bf16_f32 v32, v120, s0
	v_lshl_add_u64 v[30:31], v[0:1], 0, v[30:31]
	flat_store_short v[30:31], v32
	v_or_b32_e32 v32, 27, v72
	v_ashrrev_i32_e32 v33, 31, v32
	v_lshlrev_b64 v[32:33], 12, v[32:33]
	v_cvt_pk_bf16_f32 v34, v121, s0
	v_lshl_add_u64 v[32:33], v[0:1], 0, v[32:33]
	flat_store_short v[32:33], v34
	v_cvt_pk_bf16_f32 v34, v118, s0
	flat_store_short v[2:3], v34 offset:64
	v_cvt_pk_bf16_f32 v2, v119, s0
	flat_store_short v[4:5], v2 offset:64
	v_cvt_pk_bf16_f32 v2, v116, s0
	flat_store_short v[6:7], v2 offset:64
	v_cvt_pk_bf16_f32 v2, v117, s0
	flat_store_short v[8:9], v2 offset:64
	v_cvt_pk_bf16_f32 v2, v114, s0
	flat_store_short v[10:11], v2 offset:64
	v_cvt_pk_bf16_f32 v2, v115, s0
	flat_store_short v[12:13], v2 offset:64
	v_cvt_pk_bf16_f32 v2, v112, s0
	flat_store_short v[14:15], v2 offset:64
	v_cvt_pk_bf16_f32 v2, v113, s0
	flat_store_short v[16:17], v2 offset:64
	v_cvt_pk_bf16_f32 v2, v110, s0
	flat_store_short v[18:19], v2 offset:64
	v_cvt_pk_bf16_f32 v2, v111, s0
	flat_store_short v[20:21], v2 offset:64
	v_cvt_pk_bf16_f32 v2, v108, s0
	flat_store_short v[22:23], v2 offset:64
	v_cvt_pk_bf16_f32 v2, v109, s0
	flat_store_short v[24:25], v2 offset:64
	v_cvt_pk_bf16_f32 v2, v106, s0
	flat_store_short v[26:27], v2 offset:64
	v_cvt_pk_bf16_f32 v2, v107, s0
	flat_store_short v[28:29], v2 offset:64
	v_cvt_pk_bf16_f32 v2, v104, s0
	flat_store_short v[30:31], v2 offset:64
	v_cvt_pk_bf16_f32 v2, v105, s0
; DI bfr f2bf(float a) { return (bfr)(pk2(a, 0.f) & 0xffffu); }
; DI int crow(int r, int h) { return (r & 3) + 8 * (r >> 2) + 4 * h; }
; DI void phase_merge(const Params& p, int l, unsigned char* smem) {
;     ...
; #pragma unroll
;     for (int mi = 0; mi < 2; ++mi)
; #pragma unroll
;       for (int ni = 0; ni < 2; ++ni) {
;         const int col = n0 + wn * 64 + ni * 32 + l31, rb = m0 + wm * 64 + mi * 32;
; #pragma unroll
;         for (int r = 0; r < 16; ++r) Y[(size_t)(rb + crow(r, h)) * DM + col] = f2bf(tot[mi][ni][r]);
	v_ashrrev_i32_e32 v97, 31, v96
	flat_store_short v[32:33], v2 offset:64
	v_lshlrev_b64 v[2:3], 12, v[96:97]
	v_cvt_pk_bf16_f32 v4, v102, s0
	v_lshl_add_u64 v[2:3], v[0:1], 0, v[2:3]
	flat_store_short v[2:3], v4
	v_or_b32_e32 v4, 33, v72
	v_ashrrev_i32_e32 v5, 31, v4
	v_lshlrev_b64 v[4:5], 12, v[4:5]
	v_cvt_pk_bf16_f32 v6, v103, s0
	v_lshl_add_u64 v[4:5], v[0:1], 0, v[4:5]
	flat_store_short v[4:5], v6
	v_or_b32_e32 v6, 34, v72
	v_ashrrev_i32_e32 v7, 31, v6
	v_lshlrev_b64 v[6:7], 12, v[6:7]
	v_cvt_pk_bf16_f32 v8, v100, s0
	v_lshl_add_u64 v[6:7], v[0:1], 0, v[6:7]
	flat_store_short v[6:7], v8
	v_or_b32_e32 v8, 35, v72
	v_ashrrev_i32_e32 v9, 31, v8
	v_lshlrev_b64 v[8:9], 12, v[8:9]
	v_cvt_pk_bf16_f32 v10, v101, s0
	v_lshl_add_u64 v[8:9], v[0:1], 0, v[8:9]
	flat_store_short v[8:9], v10
	v_or_b32_e32 v10, 40, v72
	v_ashrrev_i32_e32 v11, 31, v10
	v_lshlrev_b64 v[10:11], 12, v[10:11]
	v_cvt_pk_bf16_f32 v12, v98, s0
	v_lshl_add_u64 v[10:11], v[0:1], 0, v[10:11]
	flat_store_short v[10:11], v12
	v_or_b32_e32 v12, 41, v72
	v_ashrrev_i32_e32 v13, 31, v12
	v_lshlrev_b64 v[12:13], 12, v[12:13]
	v_cvt_pk_bf16_f32 v14, v99, s0
	v_lshl_add_u64 v[12:13], v[0:1], 0, v[12:13]
	flat_store_short v[12:13], v14
	v_or_b32_e32 v14, 42, v72
	v_ashrrev_i32_e32 v15, 31, v14
	v_lshlrev_b64 v[14:15], 12, v[14:15]
	v_cvt_pk_bf16_f32 v16, v94, s0
	v_lshl_add_u64 v[14:15], v[0:1], 0, v[14:15]
	flat_store_short v[14:15], v16
	v_or_b32_e32 v16, 43, v72
	v_ashrrev_i32_e32 v17, 31, v16
	v_lshlrev_b64 v[16:17], 12, v[16:17]
	v_cvt_pk_bf16_f32 v18, v95, s0
	v_lshl_add_u64 v[16:17], v[0:1], 0, v[16:17]
	flat_store_short v[16:17], v18
	v_or_b32_e32 v18, 48, v72
	v_ashrrev_i32_e32 v19, 31, v18
	v_lshlrev_b64 v[18:19], 12, v[18:19]
	v_cvt_pk_bf16_f32 v20, v92, s0
	v_lshl_add_u64 v[18:19], v[0:1], 0, v[18:19]
	flat_store_short v[18:19], v20
	v_or_b32_e32 v20, 49, v72
	v_ashrrev_i32_e32 v21, 31, v20
	v_lshlrev_b64 v[20:21], 12, v[20:21]
	v_cvt_pk_bf16_f32 v22, v93, s0
	v_lshl_add_u64 v[20:21], v[0:1], 0, v[20:21]
	flat_store_short v[20:21], v22
	v_or_b32_e32 v22, 50, v72
	v_ashrrev_i32_e32 v23, 31, v22
	v_lshlrev_b64 v[22:23], 12, v[22:23]
	v_cvt_pk_bf16_f32 v24, v90, s0
	v_lshl_add_u64 v[22:23], v[0:1], 0, v[22:23]
	flat_store_short v[22:23], v24
	v_or_b32_e32 v24, 51, v72
	v_ashrrev_i32_e32 v25, 31, v24
	v_lshlrev_b64 v[24:25], 12, v[24:25]
	v_cvt_pk_bf16_f32 v26, v91, s0
	v_lshl_add_u64 v[24:25], v[0:1], 0, v[24:25]
	flat_store_short v[24:25], v26
	v_or_b32_e32 v26, 56, v72
	v_ashrrev_i32_e32 v27, 31, v26
	v_lshlrev_b64 v[26:27], 12, v[26:27]
	v_cvt_pk_bf16_f32 v28, v88, s0
	v_lshl_add_u64 v[26:27], v[0:1], 0, v[26:27]
	flat_store_short v[26:27], v28
	v_or_b32_e32 v28, 57, v72
	v_ashrrev_i32_e32 v29, 31, v28
	v_lshlrev_b64 v[28:29], 12, v[28:29]
	v_cvt_pk_bf16_f32 v30, v89, s0
	v_lshl_add_u64 v[28:29], v[0:1], 0, v[28:29]
	flat_store_short v[28:29], v30
	v_or_b32_e32 v30, 58, v72
	v_ashrrev_i32_e32 v31, 31, v30
	v_lshlrev_b64 v[30:31], 12, v[30:31]
	v_cvt_pk_bf16_f32 v32, v86, s0
	v_lshl_add_u64 v[30:31], v[0:1], 0, v[30:31]
	flat_store_short v[30:31], v32
	v_or_b32_e32 v32, 59, v72
	v_ashrrev_i32_e32 v33, 31, v32
	v_lshlrev_b64 v[32:33], 12, v[32:33]
	v_lshl_add_u64 v[0:1], v[0:1], 0, v[32:33]
	v_cvt_pk_bf16_f32 v32, v84, s0
	flat_store_short v[2:3], v32 offset:64
	v_cvt_pk_bf16_f32 v2, v85, s0
	flat_store_short v[4:5], v2 offset:64
	v_cvt_pk_bf16_f32 v2, v82, s0
	flat_store_short v[6:7], v2 offset:64
	v_cvt_pk_bf16_f32 v2, v83, s0
	flat_store_short v[8:9], v2 offset:64
	v_cvt_pk_bf16_f32 v2, v80, s0
	flat_store_short v[10:11], v2 offset:64
	v_cvt_pk_bf16_f32 v2, v81, s0
	flat_store_short v[12:13], v2 offset:64
	v_cvt_pk_bf16_f32 v2, v78, s0
	flat_store_short v[14:15], v2 offset:64
	v_cvt_pk_bf16_f32 v2, v79, s0
	flat_store_short v[16:17], v2 offset:64
	v_cvt_pk_bf16_f32 v2, v76, s0
	flat_store_short v[18:19], v2 offset:64
	v_cvt_pk_bf16_f32 v2, v77, s0
	flat_store_short v[20:21], v2 offset:64
	v_cvt_pk_bf16_f32 v2, v74, s0
	flat_store_short v[22:23], v2 offset:64
	v_cvt_pk_bf16_f32 v2, v75, s0
	flat_store_short v[24:25], v2 offset:64
	v_cvt_pk_bf16_f32 v2, v70, s0
	flat_store_short v[26:27], v2 offset:64
	v_cvt_pk_bf16_f32 v2, v71, s0
	flat_store_short v[28:29], v2 offset:64
	v_cvt_pk_bf16_f32 v2, v68, s0
	v_cvt_pk_bf16_f32 v34, v87, s0
	flat_store_short v[30:31], v2 offset:64
	v_cvt_pk_bf16_f32 v2, v69, s0
	s_mov_b32 s14, 0
	flat_store_short v[0:1], v34
	flat_store_short v[0:1], v2 offset:64
